# P2 interleave aligned to heads: all 16 workgroups of one head run NA first, the other head's run diff first (vcu bit 4)
# speedup vs baseline: 1.0025x; 1.0025x over previous
; __global__ void __launch_bounds__(NWAVES * 64, 2) mega_fwd(Args args) {
;     ...
;     if (IN(2)) {
;         const float d1 = wave_sum(lq1[lane] * lk1[lane]), d2 = wave_sum(lq2[lane] * lk2[lane]);
;         const float lam = expf(d1) - expf(d2) + 0.2f;
;         const att::SideJob SJ{w_out, w_up, w_dn, g_mlp, WOUT, WUP, WDN, vcu, 256, (G == 256) ? 36 : 0};
;         for (int u = vcu; u < BATCH * NHEAD * 16; u += G) {
;             const int bh = u >> 4, qb = u & 15;
;             datt::diff_unit2<8>(PROJ, KBI, VBI, out, MIX, subg, lam, bh >> 3, bh & 7, qb, (char*)lds + RING_OFF, SJ, (const unsigned*)(ctl + CW_P1D), (G == 256 && N_LAUNCHES != PER_PHASE) ? 256u : 0u);
;         }
;         for (int u = vcu; u < BATCH * NHEAD * 16; u += G) {
;             const int bh = u >> 4, rg = u & 15;
;             att::na_unit<0>(PROJ, MIX, relb, bh >> 3, bh & 7, rg, (char*)lds + RING_OFF);
;         }
.LBB0_395:
	v_readlane_b32 s4, v242, 6
	v_readlane_b32 s5, v242, 7
	s_cmp_lt_i32 s4, 3
	s_cselect_b64 s[0:1], -1, 0
	s_cmp_gt_i32 s5, 2
	s_cselect_b64 s[2:3], -1, 0
	s_and_b64 s[0:1], s[0:1], s[2:3]
	s_andn2_b64 vcc, exec, s[0:1]
	s_cbranch_vccnz .LBB0_628
	v_writelane_b32 v242, 0, 62
	s_bitcmp1_b32 s76, 4
	s_cbranch_scc1 .Lp2_nafirst
